# sample attention V tile: 4 wide row loads per wave, bf16 tile in LDS shared by the 4 waves of a key split, fragments fetched with transposed LDS reads (6 global loads per wave-step instead of 18)
# speedup vs baseline: 1.0016x; 1.0016x over previous
; __device__ __forceinline__ void sattn_unit(const Args& a, LAS unsigned char* lds, const LAS float* bt, int db, int h, int t, int tid, int wave, int lane) {
;     ...
;     for (int it = 0; it < nf; ++it) {
;         const int key0 = __builtin_amdgcn_readfirstlane((tile0 + it) * 32);
;         bf16x8 kf[4]; bf16x8 vf[2][2];
;         SA_CVT();
;         if (it + 1 < nf) SA_LOAD(key0 + 32);
.Lks_m0:
	v_readlane_b32 s34, v251, 10
	v_mbcnt_lo_u32_b32 v250, -1, 0
	v_mbcnt_hi_u32_b32 v250, -1, v250
	s_lshr_b32 s14, s34, 2
	s_lshl_b32 s14, s14, 14
	s_add_i32 s14, s14, 0x12800
	s_bfe_u32 s15, s34, 0x10001
	s_lshl_b32 s15, s15, 12
	s_add_i32 s15, s15, s14
	v_lshrrev_b32_e32 v74, 5, v250
	v_and_b32_e32 v75, 31, v250
	v_lshlrev_b32_e32 v73, 8, v74
	v_lshl_add_u32 v73, v75, 1, v73
	v_add_u32_e32 v73, s15, v73
	v_cvt_pk_bf16_f32 v72, v176, v176
	ds_write_b16 v73, v72 offset:0
	v_cvt_pk_bf16_f32 v72, v179, v179
	ds_write_b16 v73, v72 offset:64
	v_cvt_pk_bf16_f32 v72, v195, v195
	ds_write_b16 v73, v72 offset:128
	v_cvt_pk_bf16_f32 v72, v204, v204
	ds_write_b16 v73, v72 offset:192
	v_cvt_pk_bf16_f32 v72, v219, v219
	ds_write_b16 v73, v72 offset:512
	v_cvt_pk_bf16_f32 v72, v228, v228
	ds_write_b16 v73, v72 offset:576
	v_cvt_pk_bf16_f32 v72, v239, v239
	ds_write_b16 v73, v72 offset:640
	v_cvt_pk_bf16_f32 v72, v242, v242
	ds_write_b16 v73, v72 offset:704
	v_cvt_pk_bf16_f32 v72, v175, v175
	ds_write_b16 v73, v72 offset:1024
	v_cvt_pk_bf16_f32 v72, v178, v178
	ds_write_b16 v73, v72 offset:1088
	v_cvt_pk_bf16_f32 v72, v186, v186
	ds_write_b16 v73, v72 offset:1152
	v_cvt_pk_bf16_f32 v72, v202, v202
	ds_write_b16 v73, v72 offset:1216
	v_cvt_pk_bf16_f32 v72, v218, v218
	ds_write_b16 v73, v72 offset:1536
	v_cvt_pk_bf16_f32 v72, v226, v226
	ds_write_b16 v73, v72 offset:1600
	v_cvt_pk_bf16_f32 v72, v238, v238
	ds_write_b16 v73, v72 offset:1664
	v_cvt_pk_bf16_f32 v72, v241, v241
	ds_write_b16 v73, v72 offset:1728
	v_cvt_pk_bf16_f32 v72, v174, v174
	ds_write_b16 v73, v72 offset:2048
	v_cvt_pk_bf16_f32 v72, v177, v177
	ds_write_b16 v73, v72 offset:2112
	v_cvt_pk_bf16_f32 v72, v184, v184
	ds_write_b16 v73, v72 offset:2176
	v_cvt_pk_bf16_f32 v72, v200, v200
	ds_write_b16 v73, v72 offset:2240
	v_cvt_pk_bf16_f32 v72, v216, v216
	ds_write_b16 v73, v72 offset:2560
	v_cvt_pk_bf16_f32 v72, v224, v224
	ds_write_b16 v73, v72 offset:2624
	v_cvt_pk_bf16_f32 v72, v237, v237
	ds_write_b16 v73, v72 offset:2688
	v_cvt_pk_bf16_f32 v72, v240, v240
	ds_write_b16 v73, v72 offset:2752
	v_cvt_pk_bf16_f32 v72, v173, v173
	ds_write_b16 v73, v72 offset:3072
	v_cvt_pk_bf16_f32 v72, v180, v180
	ds_write_b16 v73, v72 offset:3136
	v_cvt_pk_bf16_f32 v72, v183, v183
	ds_write_b16 v73, v72 offset:3200
	v_cvt_pk_bf16_f32 v72, v207, v207
	ds_write_b16 v73, v72 offset:3264
	v_cvt_pk_bf16_f32 v72, v214, v214
	ds_write_b16 v73, v72 offset:3584
	v_cvt_pk_bf16_f32 v72, v231, v231
	ds_write_b16 v73, v72 offset:3648
	v_cvt_pk_bf16_f32 v72, v236, v236
	ds_write_b16 v73, v72 offset:3712
	v_cvt_pk_bf16_f32 v72, v243, v243
	ds_write_b16 v73, v72 offset:3776
	v_bfe_u32 v76, v250, 4, 1
	v_lshlrev_b32_e32 v76, 5, v76
	v_and_b32_e32 v77, 3, v250
	v_lshl_add_u32 v76, v77, 3, v76
	v_bfe_u32 v77, v250, 2, 2
	v_lshl_add_u32 v77, v74, 2, v77
	v_lshl_add_u32 v249, v77, 6, v76
	v_add_u32_e32 v249, s15, v249
	s_and_b32 s15, s34, 3
	s_lshl_b32 s48, s15, 9
	s_add_i32 s48, s48, s14
	v_lshrrev_b32_e32 v76, 3, v75
	v_lshlrev_b32_e32 v76, 11, v76
	v_lshl_add_u32 v76, v74, 6, v76
	v_and_b32_e32 v77, 7, v250
	v_lshl_add_u32 v248, v77, 3, v76
	v_add_u32_e32 v248, s48, v248
	s_lshl_b32 s15, s15, 15
	v_lshlrev_b32_e32 v76, 12, v74
	v_lshl_add_u32 v250, v75, 4, v76
	v_add_u32_e32 v250, s15, v250
	s_mov_b32 s34, 0x2000
	s_lshl_b32 s81, s81, 15
	s_movk_i32 s32, 0x2200
.LBB0_295:
	ds_write_b128 v172, v[64:67] offset:40960
	ds_write_b128 v172, v[68:71] offset:42048
	s_waitcnt lgkmcnt(0)
	s_barrier
	ds_read_b64_tr_b16 v[72:73], v249
	ds_read_b64_tr_b16 v[74:75], v249 offset:512
	ds_read_b64_tr_b16 v[76:77], v249 offset:1024
	ds_read_b64_tr_b16 v[78:79], v249 offset:1536
	ds_read_b64_tr_b16 v[80:81], v249 offset:2048
	ds_read_b64_tr_b16 v[82:83], v249 offset:2560
	ds_read_b64_tr_b16 v[84:85], v249 offset:3072
	ds_read_b64_tr_b16 v[86:87], v249 offset:3584
	ds_read_b128 v[108:111], v170 offset:40960
	ds_read_b128 v[104:107], v170 offset:40976
	ds_read_b128 v[100:103], v170 offset:41024
	ds_read_b128 v[96:99], v170 offset:41040
	ds_read_b128 v[44:47], v170 offset:41088
	ds_read_b128 v[40:43], v170 offset:41104
	ds_read_b128 v[36:39], v170 offset:41152
	ds_read_b128 v[32:35], v170 offset:41168
	v_add_u32_e32 v170, s32, v170
	v_add_u32_e32 v172, s32, v172
	s_sub_i32 s32, 0, s32
	v_add_u32_e32 v249, s34, v249
	v_add_u32_e32 v248, s34, v248
	s_sub_i32 s34, 0, s34
	s_add_i32 s0, s96, s35
	s_lshl_b32 vcc_lo, s0, 5
	s_add_i32 s35, s35, 1
	s_cmp_ge_u32 s35, s97
	s_cbranch_scc1 .LBB0_297
	s_add_i32 s0, s30, vcc_lo
	s_ashr_i32 s1, s0, 31
	s_lshl_b64 s[0:1], s[0:1], 12
	s_lshl_b32 s14, s5, 2
	s_or_b32 s0, s0, s14
	s_add_u32 s48, s93, s0
	s_addc_u32 s49, s89, s1
	s_add_u32 s48, s48, s81
	s_addc_u32 s49, s49, 0
	s_add_u32 s0, s42, s0
	s_addc_u32 s1, s43, s1
	v_lshl_add_u64 v[64:65], v[112:113], 2, s[48:49]
	v_lshl_add_u64 v[68:69], v[120:121], 2, s[48:49]
	global_load_dwordx4 v[64:67], v[64:65], off
	s_nop 0
	global_load_dwordx4 v[68:71], v[68:69], off
	s_nop 0
	global_load_dwordx4 v[196:199], v250, s[0:1]
	s_add_u32 s14, s0, 0x2000
	s_addc_u32 s15, s1, 0
	global_load_dwordx4 v[200:203], v250, s[14:15]
	s_add_u32 s48, s0, 0x4000
	s_addc_u32 s49, s1, 0
	global_load_dwordx4 v[204:207], v250, s[48:49]
	s_add_u32 s14, s0, 0x6000
	s_addc_u32 s15, s1, 0
	global_load_dwordx4 v[208:211], v250, s[14:15]

.LBB0_301:
	v_sub_f32_e32 v32, v32, v104
	v_exp_f32_e32 v32, v32
	v_sub_f32_e32 v33, v33, v104
	v_exp_f32_e32 v33, v33
	v_sub_f32_e32 v34, v34, v104
	v_exp_f32_e32 v34, v34
	v_sub_f32_e32 v35, v35, v104
	v_sub_f32_e32 v36, v36, v104
	v_sub_f32_e32 v37, v37, v104
	v_sub_f32_e32 v38, v38, v104
	v_sub_f32_e32 v39, v39, v104
	v_exp_f32_e32 v35, v35
	v_exp_f32_e32 v36, v36
	v_exp_f32_e32 v37, v37
	v_exp_f32_e32 v38, v38
	v_exp_f32_e32 v39, v39
	v_add_f32_e32 v105, 0, v32
	v_add_f32_e32 v105, v33, v105
	v_add_f32_e32 v105, v34, v105
	v_add_f32_e32 v105, v35, v105
	v_cvt_pk_bf16_f32 v32, v32, v33
	v_cvt_pk_bf16_f32 v33, v34, v35
	v_cvt_pk_bf16_f32 v34, v36, v37
	v_cvt_pk_bf16_f32 v35, v38, v39
	v_sub_f32_e32 v40, v40, v104
	v_sub_f32_e32 v41, v41, v104
	v_sub_f32_e32 v42, v42, v104
	v_sub_f32_e32 v43, v43, v104
	v_sub_f32_e32 v44, v44, v104
	v_sub_f32_e32 v45, v45, v104
	v_sub_f32_e32 v46, v46, v104
	v_sub_f32_e32 v47, v47, v104
	v_exp_f32_e32 v40, v40
	v_exp_f32_e32 v41, v41
	v_exp_f32_e32 v42, v42
	v_exp_f32_e32 v43, v43
	v_exp_f32_e32 v44, v44
	v_exp_f32_e32 v45, v45
	v_exp_f32_e32 v46, v46
	v_exp_f32_e32 v47, v47
	v_add_f32_e32 v105, v36, v105
	v_mfma_f32_32x32x16_bf16 v[0:15], v[32:35], v[72:75], v[0:15]
	v_add_f32_e32 v105, v37, v105
	v_add_f32_e32 v105, v38, v105
	v_add_f32_e32 v105, v39, v105
	v_cvt_pk_bf16_f32 v36, v40, v41
	v_cvt_pk_bf16_f32 v37, v42, v43
	v_cvt_pk_bf16_f32 v38, v44, v45
	v_cvt_pk_bf16_f32 v39, v46, v47
	v_mfma_f32_32x32x16_bf16 v[16:31], v[32:35], v[80:83], v[16:31]
	v_add_f32_e32 v105, v40, v105
	v_add_f32_e32 v105, v41, v105
	v_mfma_f32_32x32x16_bf16 v[0:15], v[36:39], v[76:79], v[0:15]
	v_add_f32_e32 v105, v42, v105
	v_add_f32_e32 v105, v43, v105
	v_add_f32_e32 v105, v44, v105
	v_add_f32_e32 v105, v45, v105
	v_add_f32_e32 v105, v46, v105
	v_add_f32_e32 v105, v47, v105
	v_add_f32_e32 v169, v105, v169
	v_mfma_f32_32x32x16_bf16 v[16:31], v[36:39], v[84:87], v[16:31]
	s_cmp_eq_u32 s97, s35
	s_cbranch_scc1 .LBB0_303
	s_waitcnt vmcnt(0)
	v_cvt_pk_bf16_f32 v88, v196, v197
	v_cvt_pk_bf16_f32 v89, v198, v199
	v_cvt_pk_bf16_f32 v90, v200, v201
	v_cvt_pk_bf16_f32 v91, v202, v203
	v_cvt_pk_bf16_f32 v92, v204, v205
	v_cvt_pk_bf16_f32 v93, v206, v207
	v_cvt_pk_bf16_f32 v94, v208, v209
	v_cvt_pk_bf16_f32 v95, v210, v211
	ds_write_b64 v248, v[88:89]
	ds_write_b64 v248, v[90:91] offset:128
	ds_write_b64 v248, v[92:93] offset:256
	ds_write_b64 v248, v[94:95] offset:384
	v_mov_b32_e32 v244, v104
	s_branch .LBB0_295
